# 8-byte global stores (row-pass h, mid) also write-through sc0 sc1, on top of the 16-byte ones
# speedup vs baseline: 1.0053x; 1.0049x over previous
; template <int MODE> ...
;     for (int m = RPW * gw; m < M_TOK; m += RPW * NGW) {
;         f32x4 xv[RPW][8]; v2u yy[RPW][8];
; #pragma unroll
;         for (int rr = 0; rr < RPW; ++rr) {
;             const float* xr = ((MODE == 0 || xin != nullptr) ? xin : xres) + (size_t)(m + rr) * DM + lane * 4;
; #pragma unroll
;             for (int k = 0; k < 8; ++k) xv[rr][k] = *(const f32x4*)(xr + k * 256);
;     ...
;         if (MODE <= 1) {
;             float rstd[RPW];
; #pragma unroll
;             for (int rr = 0; rr < RPW; ++rr) { float s = 0.f;
; #pragma unroll
;                 for (int k = 0; k < 8; ++k) s += (xv[rr][k][0] * xv[rr][k][0] + xv[rr][k][1] * xv[rr][k][1]) + (xv[rr][k][2] * xv[rr][k][2] + xv[rr][k][3] * xv[rr][k][3]);
;                 rstd[rr] = 1.0f / sqrtf(wave_sum(s) * (1.f / DM) + RMS_EPS); }
.LBB0_137:
	global_load_dwordx4 v[46:49], v[68:69], off offset:-4096
	global_load_dwordx4 v[42:45], v[68:69], off offset:-3072
	global_load_dwordx4 v[38:41], v[68:69], off offset:-2048
	global_load_dwordx4 v[34:37], v[68:69], off offset:-1024
	v_add_co_u32_e32 v70, vcc, 0xffffe000, v68
	global_load_dwordx4 v[54:57], v[68:69], off
	global_load_dwordx4 v[50:53], v[68:69], off offset:1024
	global_load_dwordx4 v[62:65], v[68:69], off offset:2048
	global_load_dwordx4 v[58:61], v[68:69], off offset:3072
	v_addc_co_u32_e32 v71, vcc, -1, v69, vcc
	global_load_dwordx4 v[88:91], v[70:71], off
	v_add_co_u32_e32 v104, vcc, 0xfffff000, v68
	v_add_co_u32_e64 v72, s[4:5], s16, v66
	s_nop 0
	v_addc_co_u32_e32 v105, vcc, -1, v69, vcc
	v_add_co_u32_e32 v70, vcc, s0, v68
	global_load_dwordx4 v[92:95], v[104:105], off offset:-3072
	global_load_dwordx4 v[96:99], v[104:105], off offset:-2048
	global_load_dwordx4 v[100:103], v[104:105], off offset:-1024
	v_addc_co_u32_e32 v71, vcc, 0, v69, vcc
	global_load_dwordx4 v[104:107], v[70:71], off
	global_load_dwordx4 v[108:111], v[70:71], off offset:1024
	global_load_dwordx4 v[112:115], v[70:71], off offset:2048
	global_load_dwordx4 v[116:119], v[70:71], off offset:3072
	v_addc_co_u32_e64 v73, s[4:5], -1, v67, s[4:5]
	v_add_co_u32_e64 v74, s[4:5], s17, v66
	s_add_i32 s8, s8, s10
	s_nop 0
	v_addc_co_u32_e64 v75, s[4:5], -1, v67, s[4:5]
	v_add_co_u32_e64 v76, s[4:5], s18, v66
	s_cmpk_gt_i32 s8, 0x3fff
	s_nop 0
	v_addc_co_u32_e64 v77, s[4:5], -1, v67, s[4:5]
	v_add_co_u32_e64 v78, s[4:5], s19, v66
	v_lshl_add_u64 v[68:69], v[68:69], 0, s[14:15]
	s_nop 0
	v_addc_co_u32_e64 v79, s[4:5], -1, v67, s[4:5]
	v_add_co_u32_e64 v80, s[4:5], s20, v66
	s_waitcnt vmcnt(15)
	v_mul_f32_e32 v70, v47, v47
	v_mul_f32_e32 v71, v49, v49
	s_waitcnt vmcnt(14)
	v_mul_f32_e32 v87, v43, v43
	v_mul_f32_e32 v120, v45, v45
	s_waitcnt vmcnt(13)
	v_mul_f32_e32 v121, v39, v39
	v_mul_f32_e32 v122, v41, v41
	s_waitcnt vmcnt(12)
	v_mul_f32_e32 v123, v35, v35
	v_mul_f32_e32 v124, v37, v37
	s_waitcnt vmcnt(11)
	v_mul_f32_e32 v125, v55, v55
	v_mul_f32_e32 v126, v57, v57
	s_waitcnt vmcnt(10)
	v_mul_f32_e32 v127, v51, v51
	v_mul_f32_e32 v128, v53, v53
	s_waitcnt vmcnt(9)
	v_mul_f32_e32 v129, v63, v63
	v_mul_f32_e32 v130, v65, v65
	v_fmac_f32_e32 v70, v46, v46
	v_fmac_f32_e32 v71, v48, v48
	v_fmac_f32_e32 v87, v42, v42
	v_fmac_f32_e32 v120, v44, v44
	v_fmac_f32_e32 v121, v38, v38
	v_fmac_f32_e32 v122, v40, v40
	v_fmac_f32_e32 v123, v34, v34
	v_fmac_f32_e32 v124, v36, v36
	v_fmac_f32_e32 v125, v54, v54
	v_fmac_f32_e32 v126, v56, v56
	v_fmac_f32_e32 v127, v50, v50
	v_fmac_f32_e32 v128, v52, v52
	v_fmac_f32_e32 v129, v62, v62
	v_fmac_f32_e32 v130, v64, v64
	v_add_f32_e32 v70, v70, v71
	s_waitcnt vmcnt(7)
	v_mul_f32_e32 v71, v89, v89
	v_add_f32_e32 v87, v87, v120
	v_mul_f32_e32 v120, v91, v91
	v_add_f32_e32 v121, v121, v122
	v_add_f32_e32 v122, v123, v124
	v_add_f32_e32 v123, v125, v126
	v_add_f32_e32 v124, v127, v128
	v_mul_f32_e32 v131, v59, v59
	v_mul_f32_e32 v132, v61, v61
	v_add_f32_e32 v125, v129, v130
	v_fmac_f32_e32 v71, v88, v88
	v_fmac_f32_e32 v120, v90, v90
	s_waitcnt vmcnt(6)
	v_mul_f32_e32 v127, v93, v93
	v_mul_f32_e32 v128, v95, v95
	v_add_f32_e32 v123, v123, v124
	v_fmac_f32_e32 v131, v58, v58
	v_fmac_f32_e32 v132, v60, v60
	s_waitcnt vmcnt(5)
	v_mul_f32_e32 v129, v97, v97
	v_mul_f32_e32 v130, v99, v99
	v_add_f32_e32 v71, v71, v120
	v_fmac_f32_e32 v127, v92, v92
	v_fmac_f32_e32 v128, v94, v94
	v_add_f32_e32 v120, v123, v125
	s_waitcnt vmcnt(3)
	v_mul_f32_e32 v123, v105, v105
	v_mul_f32_e32 v124, v107, v107
	v_add_f32_e32 v126, v131, v132
	v_mul_f32_e32 v131, v101, v101
	v_mul_f32_e32 v132, v103, v103
	v_fmac_f32_e32 v129, v96, v96
	v_fmac_f32_e32 v130, v98, v98
	s_waitcnt vmcnt(2)
	v_mul_f32_e32 v125, v109, v109
	v_mul_f32_e32 v133, v111, v111
	v_add_f32_e32 v127, v127, v128
	v_fmac_f32_e32 v123, v104, v104
	v_fmac_f32_e32 v124, v106, v106
	v_fmac_f32_e32 v131, v100, v100
	v_fmac_f32_e32 v132, v102, v102
	s_waitcnt vmcnt(1)
	v_mul_f32_e32 v134, v113, v113
	v_mul_f32_e32 v135, v115, v115
	v_add_f32_e32 v128, v129, v130
	v_add_f32_e32 v120, v120, v126
	v_fmac_f32_e32 v125, v108, v108
	v_fmac_f32_e32 v133, v110, v110
	v_add_f32_e32 v71, v71, v127
	v_add_f32_e32 v123, v123, v124
	s_waitcnt vmcnt(0)
; template <int MODE> ...
;     ...
;             for (int rr = 0; rr < RPW; ++rr) { float s = 0.f;
; #pragma unroll
;                 for (int k = 0; k < 8; ++k) s += (xv[rr][k][0] * xv[rr][k][0] + xv[rr][k][1] * xv[rr][k][1]) + (xv[rr][k][2] * xv[rr][k][2] + xv[rr][k][3] * xv[rr][k][3]);
;                 rstd[rr] = 1.0f / sqrtf(wave_sum(s) * (1.f / DM) + RMS_EPS); }
; #pragma unroll
;             for (int k = 0; k < 8; ++k) { const f32x4 g = *(const f32x4*)(gpre + k * 256 + lane * 4);
; #pragma unroll
;                 for (int rr = 0; rr < RPW; ++rr) { const f32x4 a = xv[rr][k] * rstd[rr] * g;
	v_mul_f32_e32 v136, v117, v117
	v_mul_f32_e32 v137, v119, v119
	v_add_f32_e32 v129, v131, v132
	v_fmac_f32_e32 v134, v112, v112
	v_fmac_f32_e32 v135, v114, v114
	v_add_f32_e32 v124, v125, v133
	v_add_f32_e32 v71, v71, v128
	v_add_f32_e32 v120, v120, v123
	v_fmac_f32_e32 v136, v116, v116
	v_fmac_f32_e32 v137, v118, v118
	v_add_f32_e32 v125, v134, v135
	v_add_f32_e32 v71, v71, v129
	v_add_f32_e32 v120, v120, v124
	v_add_f32_e32 v126, v136, v137
	v_add_f32_e32 v70, v71, v70
	v_add_f32_e32 v71, v120, v125
	v_add_f32_e32 v70, v70, v87
	v_add_f32_e32 v71, v71, v126
	v_add_f32_e32 v70, v70, v121
	v_add_f32_e32 v70, v70, v122
	v_add_f32_dpp v71, v71, v71 quad_perm:[1,0,3,2] row_mask:0xf bank_mask:0xf bound_ctrl:1
	v_addc_co_u32_e64 v81, s[4:5], -1, v67, s[4:5]
	s_nop 0
	v_add_f32_dpp v71, v71, v71 quad_perm:[2,3,0,1] row_mask:0xf bank_mask:0xf bound_ctrl:1
	v_add_f32_dpp v70, v70, v70 quad_perm:[1,0,3,2] row_mask:0xf bank_mask:0xf bound_ctrl:1
	v_add_co_u32_e64 v82, s[4:5], s21, v66
	v_add_f32_dpp v71, v71, v71 row_half_mirror row_mask:0xf bank_mask:0xf bound_ctrl:1
	v_add_f32_dpp v70, v70, v70 quad_perm:[2,3,0,1] row_mask:0xf bank_mask:0xf bound_ctrl:1
	v_addc_co_u32_e64 v83, s[4:5], -1, v67, s[4:5]
	v_add_f32_dpp v71, v71, v71 row_mirror row_mask:0xf bank_mask:0xf bound_ctrl:1
	v_add_f32_dpp v70, v70, v70 row_half_mirror row_mask:0xf bank_mask:0xf bound_ctrl:1
	v_mov_b32_e32 v87, v71
	s_nop 1
	v_permlane16_swap_b32_e32 v71, v87
	v_add_f32_dpp v70, v70, v70 row_mirror row_mask:0xf bank_mask:0xf bound_ctrl:1
	v_mov_b32_e32 v120, v70
	v_add_f32_e32 v71, v71, v87
	s_nop 0
	v_permlane16_swap_b32_e32 v70, v120
	v_mov_b32_e32 v87, v71
	v_add_f32_e32 v70, v70, v120
	s_nop 0
	v_permlane32_swap_b32_e32 v71, v87
	v_mov_b32_e32 v120, v70
	v_add_f32_e32 v71, v71, v87
	s_nop 0
	v_permlane32_swap_b32_e32 v70, v120
	v_fmamk_f32 v71, v71, 0x3a000000, v1
	v_add_co_u32_e64 v84, s[4:5], s22, v66
	v_add_f32_e32 v70, v70, v120
	v_mul_f32_e32 v87, 0x4f800000, v71
	v_cmp_gt_f32_e32 vcc, s1, v71
	v_addc_co_u32_e64 v85, s[4:5], -1, v67, s[4:5]
	v_fmamk_f32 v70, v70, 0x3a000000, v1
	v_cndmask_b32_e32 v71, v71, v87, vcc
	v_mul_f32_e32 v87, 0x4f800000, v70
	v_sqrt_f32_e32 v120, v71
	v_cmp_gt_f32_e64 s[4:5], s1, v70
	v_add_u32_e32 v121, -1, v120
	s_nop 0
	v_cndmask_b32_e64 v70, v70, v87, s[4:5]
	v_sqrt_f32_e32 v87, v70
	v_add_u32_e32 v122, 1, v120
	v_fma_f32 v123, -v121, v120, v71
	v_fma_f32 v124, -v122, v120, v71
	v_add_u32_e32 v125, -1, v87
	v_cmp_ge_f32_e64 s[6:7], 0, v123
	v_add_u32_e32 v126, 1, v87
	v_fma_f32 v123, -v126, v87, v70
	v_cndmask_b32_e64 v120, v120, v121, s[6:7]
	v_cmp_lt_f32_e64 s[6:7], 0, v124
	v_fma_f32 v121, -v125, v87, v70
	s_nop 0
	v_cndmask_b32_e64 v120, v120, v122, s[6:7]
	v_cmp_ge_f32_e64 s[6:7], 0, v121
	v_mul_f32_e32 v121, 0x37800000, v120
	v_cndmask_b32_e32 v120, v120, v121, vcc
	v_cndmask_b32_e64 v87, v87, v125, s[6:7]
	v_cmp_lt_f32_e64 s[6:7], 0, v123
	v_cmp_class_f32_e32 vcc, v71, v86
	s_nop 0
	v_cndmask_b32_e64 v87, v87, v126, s[6:7]
	v_mul_f32_e32 v121, 0x37800000, v87
	v_cndmask_b32_e32 v71, v120, v71, vcc
	v_cndmask_b32_e64 v87, v87, v121, s[4:5]
	v_cmp_class_f32_e32 vcc, v70, v86
	v_div_scale_f32 v120, s[4:5], v71, v71, 1.0
	s_nop 0
	v_cndmask_b32_e32 v70, v87, v70, vcc
	v_rcp_f32_e32 v87, v120
	v_div_scale_f32 v122, s[6:7], v70, v70, 1.0
	v_rcp_f32_e32 v124, v122
	v_fma_f32 v125, -v120, v87, 1.0
	v_div_scale_f32 v121, s[4:5], 1.0, v71, 1.0
	v_fmac_f32_e32 v87, v125, v87
	v_fma_f32 v125, -v122, v124, 1.0
	v_div_scale_f32 v123, vcc, 1.0, v70, 1.0
	v_mul_f32_e32 v126, v121, v87
	v_fmac_f32_e32 v124, v125, v124
	v_fma_f32 v125, -v120, v126, v121
	v_mul_f32_e32 v127, v123, v124
	v_fmac_f32_e32 v126, v125, v87
	v_fma_f32 v125, -v122, v127, v123
	v_fmac_f32_e32 v127, v125, v124
	v_fma_f32 v120, -v120, v126, v121
	v_fma_f32 v121, -v122, v127, v123
	v_div_fmas_f32 v121, v121, v124, v127
	s_mov_b64 vcc, s[4:5]
	v_div_fixup_f32 v70, v121, v70, 1.0
	v_div_fmas_f32 v87, v120, v87, v126
	v_pk_mul_f32 v[88:89], v[88:89], v[70:71] op_sel_hi:[1,0]
	v_pk_mul_f32 v[90:91], v[90:91], v[70:71] op_sel_hi:[1,0]
	v_pk_mul_f32 v[92:93], v[92:93], v[70:71] op_sel_hi:[1,0]
	v_pk_mul_f32 v[94:95], v[94:95], v[70:71] op_sel_hi:[1,0]
	v_pk_mul_f32 v[96:97], v[96:97], v[70:71] op_sel_hi:[1,0]
	v_pk_mul_f32 v[98:99], v[98:99], v[70:71] op_sel_hi:[1,0]
	v_pk_mul_f32 v[100:101], v[100:101], v[70:71] op_sel_hi:[1,0]
	v_pk_mul_f32 v[102:103], v[102:103], v[70:71] op_sel_hi:[1,0]
	v_pk_mul_f32 v[46:47], v[46:47], v[70:71] op_sel_hi:[1,0]
	v_pk_mul_f32 v[48:49], v[48:49], v[70:71] op_sel_hi:[1,0]
	v_pk_mul_f32 v[42:43], v[42:43], v[70:71] op_sel_hi:[1,0]
	v_pk_mul_f32 v[44:45], v[44:45], v[70:71] op_sel_hi:[1,0]
	v_pk_mul_f32 v[38:39], v[38:39], v[70:71] op_sel_hi:[1,0]
	v_pk_mul_f32 v[40:41], v[40:41], v[70:71] op_sel_hi:[1,0]
	v_pk_mul_f32 v[34:35], v[34:35], v[70:71] op_sel_hi:[1,0]
	v_pk_mul_f32 v[36:37], v[36:37], v[70:71] op_sel_hi:[1,0]
	v_div_fixup_f32 v70, v87, v71, 1.0
	v_pk_mul_f32 v[54:55], v[54:55], v[70:71] op_sel_hi:[1,0]
	v_pk_mul_f32 v[56:57], v[56:57], v[70:71] op_sel_hi:[1,0]
	v_pk_mul_f32 v[88:89], v[2:3], v[88:89]
	v_pk_mul_f32 v[90:91], v[4:5], v[90:91]
	v_pk_mul_f32 v[92:93], v[6:7], v[92:93]
	v_pk_mul_f32 v[38:39], v[26:27], v[38:39]
	v_pk_mul_f32 v[40:41], v[28:29], v[40:41]
	v_pk_mul_f32 v[34:35], v[30:31], v[34:35]
	v_pk_mul_f32 v[36:37], v[32:33], v[36:37]
	v_pk_mul_f32 v[50:51], v[50:51], v[70:71] op_sel_hi:[1,0]
	v_pk_mul_f32 v[52:53], v[52:53], v[70:71] op_sel_hi:[1,0]
	v_pk_mul_f32 v[62:63], v[62:63], v[70:71] op_sel_hi:[1,0]
	v_pk_mul_f32 v[64:65], v[64:65], v[70:71] op_sel_hi:[1,0]
	v_pk_mul_f32 v[58:59], v[58:59], v[70:71] op_sel_hi:[1,0]
; __device__ __forceinline__ unsigned pk2(float lo, float hi) { return f2bf(lo) | (f2bf(hi) << 16); }
; template <int MODE> ...
;     ...
; #pragma unroll
;             for (int k = 0; k < 8; ++k) { const f32x4 g = *(const f32x4*)(gpre + k * 256 + lane * 4);
; #pragma unroll
;                 for (int rr = 0; rr < RPW; ++rr) { const f32x4 a = xv[rr][k] * rstd[rr] * g;
;                     v2u o; o.x = pk2(a[0], a[1]); o.y = pk2(a[2], a[3]);
;                     *(v2u*)(h + ((size_t)(k * 4 + (lane >> 4)) * M_TOK + (m + rr)) * 64 + (lane & 15) * 4) = o; } }
	v_pk_mul_f32 v[60:61], v[60:61], v[70:71] op_sel_hi:[1,0]
	v_pk_mul_f32 v[104:105], v[104:105], v[70:71] op_sel_hi:[1,0]
	v_pk_mul_f32 v[106:107], v[106:107], v[70:71] op_sel_hi:[1,0]
	v_pk_mul_f32 v[108:109], v[108:109], v[70:71] op_sel_hi:[1,0]
	v_pk_mul_f32 v[110:111], v[110:111], v[70:71] op_sel_hi:[1,0]
	v_pk_mul_f32 v[112:113], v[112:113], v[70:71] op_sel_hi:[1,0]
	v_pk_mul_f32 v[114:115], v[114:115], v[70:71] op_sel_hi:[1,0]
	v_pk_mul_f32 v[116:117], v[116:117], v[70:71] op_sel_hi:[1,0]
	v_pk_mul_f32 v[70:71], v[118:119], v[70:71] op_sel_hi:[1,0]
	v_pk_mul_f32 v[94:95], v[8:9], v[94:95]
	v_pk_mul_f32 v[96:97], v[10:11], v[96:97]
	v_pk_mul_f32 v[98:99], v[12:13], v[98:99]
	v_pk_mul_f32 v[100:101], v[14:15], v[100:101]
	v_pk_mul_f32 v[102:103], v[16:17], v[102:103]
	v_pk_mul_f32 v[46:47], v[18:19], v[46:47]
	v_pk_mul_f32 v[48:49], v[20:21], v[48:49]
	v_pk_mul_f32 v[42:43], v[22:23], v[42:43]
	v_pk_mul_f32 v[44:45], v[24:25], v[44:45]
	v_bfe_u32 v87, v88, 16, 1
	v_bfe_u32 v118, v89, 16, 1
	v_bfe_u32 v119, v90, 16, 1
	v_bfe_u32 v120, v91, 16, 1
	v_bfe_u32 v121, v92, 16, 1
	v_bfe_u32 v142, v39, 16, 1
	v_bfe_u32 v143, v40, 16, 1
	v_bfe_u32 v146, v35, 16, 1
	v_bfe_u32 v147, v36, 16, 1
	v_bfe_u32 v148, v37, 16, 1
	v_pk_mul_f32 v[54:55], v[2:3], v[54:55]
	v_pk_mul_f32 v[56:57], v[4:5], v[56:57]
	v_bfe_u32 v122, v93, 16, 1
	v_bfe_u32 v123, v94, 16, 1
	v_bfe_u32 v124, v95, 16, 1
	v_bfe_u32 v125, v96, 16, 1
	v_bfe_u32 v126, v97, 16, 1
	v_bfe_u32 v127, v98, 16, 1
	v_bfe_u32 v128, v99, 16, 1
	v_bfe_u32 v129, v100, 16, 1
	v_bfe_u32 v130, v101, 16, 1
	v_bfe_u32 v131, v102, 16, 1
	v_bfe_u32 v132, v103, 16, 1
	v_bfe_u32 v133, v46, 16, 1
	v_bfe_u32 v135, v48, 16, 1
	v_bfe_u32 v137, v42, 16, 1
	v_bfe_u32 v138, v43, 16, 1
	v_bfe_u32 v139, v44, 16, 1
	v_bfe_u32 v141, v38, 16, 1
	v_bfe_u32 v144, v41, 16, 1
	v_bfe_u32 v145, v34, 16, 1
	v_pk_mul_f32 v[50:51], v[6:7], v[50:51]
	v_pk_mul_f32 v[52:53], v[8:9], v[52:53]
	v_pk_mul_f32 v[62:63], v[10:11], v[62:63]
	v_pk_mul_f32 v[64:65], v[12:13], v[64:65]
	v_pk_mul_f32 v[58:59], v[14:15], v[58:59]
	v_pk_mul_f32 v[60:61], v[16:17], v[60:61]
	v_pk_mul_f32 v[104:105], v[18:19], v[104:105]
	v_pk_mul_f32 v[106:107], v[20:21], v[106:107]
	v_pk_mul_f32 v[108:109], v[22:23], v[108:109]
	v_pk_mul_f32 v[110:111], v[24:25], v[110:111]
	v_pk_mul_f32 v[112:113], v[26:27], v[112:113]
	v_pk_mul_f32 v[114:115], v[28:29], v[114:115]
	v_pk_mul_f32 v[116:117], v[30:31], v[116:117]
	v_pk_mul_f32 v[70:71], v[32:33], v[70:71]
	v_add3_u32 v87, v88, v87, s9
	v_add3_u32 v88, v89, v118, s9
	v_add3_u32 v89, v90, v119, s9
	v_add3_u32 v90, v91, v120, s9
	v_add3_u32 v91, v92, v121, s9
	v_add3_u32 v118, v39, v142, s9
	v_add3_u32 v39, v40, v143, s9
	v_add3_u32 v120, v35, v146, s9
	v_add3_u32 v35, v36, v147, s9
	v_add3_u32 v121, v37, v148, s9
	v_bfe_u32 v36, v54, 16, 1
	v_bfe_u32 v37, v55, 16, 1
	v_bfe_u32 v40, v56, 16, 1
	v_bfe_u32 v134, v47, 16, 1
	v_bfe_u32 v136, v49, 16, 1
	v_bfe_u32 v140, v45, 16, 1
	v_add3_u32 v92, v93, v122, s9
	v_add3_u32 v93, v94, v123, s9
	v_add3_u32 v94, v95, v124, s9
	v_add3_u32 v95, v96, v125, s9
	v_add3_u32 v96, v97, v126, s9
	v_add3_u32 v97, v98, v127, s9
	v_add3_u32 v98, v99, v128, s9
	v_add3_u32 v99, v100, v129, s9
	v_add3_u32 v100, v101, v130, s9
	v_add3_u32 v101, v102, v131, s9
	v_add3_u32 v102, v103, v132, s9
	v_add3_u32 v46, v46, v133, s9
	v_add3_u32 v48, v48, v135, s9
	v_add3_u32 v42, v42, v137, s9
	v_add3_u32 v103, v43, v138, s9
	v_add3_u32 v43, v44, v139, s9
	v_add3_u32 v38, v38, v141, s9
	v_add3_u32 v119, v41, v144, s9
	v_add3_u32 v34, v34, v145, s9
	v_bfe_u32 v41, v57, 16, 1
	v_bfe_u32 v44, v50, 16, 1
	v_bfe_u32 v122, v51, 16, 1
	v_bfe_u32 v123, v52, 16, 1
	v_bfe_u32 v125, v62, 16, 1
	v_bfe_u32 v127, v64, 16, 1
	v_bfe_u32 v129, v58, 16, 1
	v_bfe_u32 v131, v60, 16, 1
	v_bfe_u32 v133, v104, 16, 1
	v_bfe_u32 v135, v106, 16, 1
	v_bfe_u32 v137, v108, 16, 1
	v_bfe_u32 v139, v110, 16, 1
	v_bfe_u32 v141, v112, 16, 1
	v_bfe_u32 v143, v114, 16, 1
	v_bfe_u32 v145, v116, 16, 1
	v_bfe_u32 v147, v70, 16, 1
	v_add3_u32 v54, v54, v36, s9
	v_add3_u32 v55, v55, v37, s9
	v_add3_u32 v56, v56, v40, s9
	v_lshrrev_b32_e32 v36, 16, v87
	v_lshrrev_b32_e32 v37, 16, v89
	v_add3_u32 v47, v47, v134, s9
	v_add3_u32 v49, v49, v136, s9
	v_add3_u32 v45, v45, v140, s9
	v_bfe_u32 v124, v53, 16, 1
	v_bfe_u32 v126, v63, 16, 1
; __device__ __forceinline__ unsigned pk2(float lo, float hi) { return f2bf(lo) | (f2bf(hi) << 16); }
; template <int MODE> ...
;     ...
; #pragma unroll
;             for (int k = 0; k < 8; ++k) { const f32x4 g = *(const f32x4*)(gpre + k * 256 + lane * 4);
; #pragma unroll
;                 for (int rr = 0; rr < RPW; ++rr) { const f32x4 a = xv[rr][k] * rstd[rr] * g;
;                     v2u o; o.x = pk2(a[0], a[1]); o.y = pk2(a[2], a[3]);
;                     *(v2u*)(h + ((size_t)(k * 4 + (lane >> 4)) * M_TOK + (m + rr)) * 64 + (lane & 15) * 4) = o; } }
;         }
	v_bfe_u32 v128, v65, 16, 1
	v_bfe_u32 v130, v59, 16, 1
	v_bfe_u32 v132, v61, 16, 1
	v_bfe_u32 v134, v105, 16, 1
	v_bfe_u32 v136, v107, 16, 1
	v_bfe_u32 v138, v109, 16, 1
	v_bfe_u32 v140, v111, 16, 1
	v_bfe_u32 v142, v113, 16, 1
	v_bfe_u32 v144, v115, 16, 1
	v_bfe_u32 v146, v117, 16, 1
	v_bfe_u32 v148, v71, 16, 1
	v_add3_u32 v57, v57, v41, s9
	v_add3_u32 v50, v50, v44, s9
	v_add3_u32 v51, v51, v122, s9
	v_add3_u32 v52, v52, v123, s9
	v_add3_u32 v62, v62, v125, s9
	v_add3_u32 v64, v64, v127, s9
	v_add3_u32 v58, v58, v129, s9
	v_add3_u32 v60, v60, v131, s9
	v_add3_u32 v104, v104, v133, s9
	v_add3_u32 v106, v106, v135, s9
	v_add3_u32 v108, v108, v137, s9
	v_add3_u32 v110, v110, v139, s9
	v_add3_u32 v112, v112, v141, s9
	v_add3_u32 v114, v114, v143, s9
	v_add3_u32 v116, v116, v145, s9
	v_add3_u32 v70, v70, v147, s9
	v_lshrrev_b32_e32 v40, 16, v91
	v_lshrrev_b32_e32 v41, 16, v93
	v_lshrrev_b32_e32 v44, 16, v95
	v_lshrrev_b32_e32 v87, 16, v97
	v_lshrrev_b32_e32 v89, 16, v99
	v_lshrrev_b32_e32 v91, 16, v101
	v_lshrrev_b32_e32 v46, 16, v46
	v_lshrrev_b32_e32 v48, 16, v48
	v_lshrrev_b32_e32 v93, 16, v42
	v_lshrrev_b32_e32 v95, 16, v43
	v_lshrrev_b32_e32 v97, 16, v38
	v_lshrrev_b32_e32 v99, 16, v39
	v_lshrrev_b32_e32 v101, 16, v34
	v_lshrrev_b32_e32 v122, 16, v35
	v_and_or_b32 v34, v88, s11, v36
	v_and_or_b32 v35, v90, s11, v37
	v_lshrrev_b32_e32 v54, 16, v54
	v_lshrrev_b32_e32 v56, 16, v56
	v_add3_u32 v53, v53, v124, s9
	v_add3_u32 v63, v63, v126, s9
	v_add3_u32 v65, v65, v128, s9
	v_add3_u32 v59, v59, v130, s9
	v_add3_u32 v61, v61, v132, s9
	v_add3_u32 v105, v105, v134, s9
	v_add3_u32 v107, v107, v136, s9
	v_add3_u32 v109, v109, v138, s9
	v_add3_u32 v111, v111, v140, s9
	v_add3_u32 v113, v113, v142, s9
	v_add3_u32 v115, v115, v144, s9
	v_add3_u32 v117, v117, v146, s9
	v_add3_u32 v71, v71, v148, s9
	v_and_or_b32 v36, v92, s11, v40
	v_and_or_b32 v37, v94, s11, v41
	v_and_or_b32 v38, v96, s11, v44
	v_and_or_b32 v39, v98, s11, v87
	v_and_or_b32 v40, v100, s11, v89
	v_and_or_b32 v41, v102, s11, v91
	v_and_or_b32 v42, v47, s11, v46
	v_and_or_b32 v43, v49, s11, v48
	v_and_or_b32 v44, v103, s11, v93
	v_and_or_b32 v45, v45, s11, v95
	v_and_or_b32 v46, v118, s11, v97
	v_and_or_b32 v47, v119, s11, v99
	v_and_or_b32 v48, v120, s11, v101
	v_and_or_b32 v49, v121, s11, v122
	v_lshrrev_b32_e32 v50, 16, v50
	v_lshrrev_b32_e32 v52, 16, v52
	v_lshrrev_b32_e32 v62, 16, v62
	v_lshrrev_b32_e32 v64, 16, v64
	v_lshrrev_b32_e32 v58, 16, v58
	v_lshrrev_b32_e32 v60, 16, v60
	v_lshrrev_b32_e32 v87, 16, v104
	v_lshrrev_b32_e32 v88, 16, v106
	v_lshrrev_b32_e32 v89, 16, v108
	v_lshrrev_b32_e32 v90, 16, v110
	v_lshrrev_b32_e32 v91, 16, v112
	v_lshrrev_b32_e32 v92, 16, v114
	v_lshrrev_b32_e32 v93, 16, v116
	v_lshrrev_b32_e32 v70, 16, v70
	global_store_dwordx2 v[72:73], v[34:35], off offset:-128 sc0 sc1
	v_and_or_b32 v34, v55, s11, v54
	v_and_or_b32 v35, v57, s11, v56
	global_store_dwordx2 v[74:75], v[36:37], off offset:-128 sc0 sc1
	v_and_or_b32 v36, v51, s11, v50
	v_and_or_b32 v37, v53, s11, v52
	global_store_dwordx2 v[76:77], v[38:39], off offset:-128 sc0 sc1
	v_and_or_b32 v38, v63, s11, v62
	v_and_or_b32 v39, v65, s11, v64
	global_store_dwordx2 v[78:79], v[40:41], off offset:-128 sc0 sc1
	v_and_or_b32 v40, v59, s11, v58
	v_and_or_b32 v41, v61, s11, v60
	global_store_dwordx2 v[80:81], v[42:43], off offset:-128 sc0 sc1
	v_and_or_b32 v42, v105, s11, v87
	v_and_or_b32 v43, v107, s11, v88
	global_store_dwordx2 v[82:83], v[44:45], off offset:-128 sc0 sc1
	v_and_or_b32 v44, v109, s11, v89
	v_and_or_b32 v45, v111, s11, v90
	global_store_dwordx2 v[84:85], v[46:47], off offset:-128 sc0 sc1
	v_and_or_b32 v46, v113, s11, v91
	v_and_or_b32 v47, v115, s11, v92
	global_store_dwordx2 v[66:67], v[48:49], off offset:-128 sc0 sc1
	v_and_or_b32 v48, v117, s11, v93
	v_and_or_b32 v49, v71, s11, v70
	global_store_dwordx2 v[72:73], v[34:35], off sc0 sc1
	global_store_dwordx2 v[74:75], v[36:37], off sc0 sc1
	global_store_dwordx2 v[76:77], v[38:39], off sc0 sc1
	global_store_dwordx2 v[78:79], v[40:41], off sc0 sc1
	global_store_dwordx2 v[80:81], v[42:43], off sc0 sc1
	global_store_dwordx2 v[82:83], v[44:45], off sc0 sc1
	global_store_dwordx2 v[84:85], v[46:47], off sc0 sc1
	global_store_dwordx2 v[66:67], v[48:49], off sc0 sc1
	v_lshl_add_u64 v[66:67], v[66:67], 0, s[12:13]
	s_cbranch_scc0 .LBB0_137

; __device__ __forceinline__ float bf2f(unsigned h) { return __uint_as_float(h << 16); }
; template <int MODE> ...
;     for (int m = RPW * gw; m < M_TOK; m += RPW * NGW) {
;         f32x4 xv[RPW][8]; v2u yy[RPW][8];
; #pragma unroll
;         for (int rr = 0; rr < RPW; ++rr) {
;             const float* xr = ((MODE == 0 || xin != nullptr) ? xin : xres) + (size_t)(m + rr) * DM + lane * 4;
; #pragma unroll
;             for (int k = 0; k < 8; ++k) xv[rr][k] = *(const f32x4*)(xr + k * 256);
;             if (MODE >= 1) { const bf16_t* yr = y + (size_t)(m + rr) * 256 + lane * 4;
; #pragma unroll
;                 for (int k = 0; k < 8; ++k) yy[rr][k] = *(const v2u*)(yr + (size_t)k * ((size_t)M_TOK * 256)); }
;         }
;         if (MODE >= 1) {
;             float rstd[RPW];
; #pragma unroll
;             for (int rr = 0; rr < RPW; ++rr) { float s = 0.f;
; #pragma unroll
;                 for (int k = 0; k < 8; ++k)
; #pragma unroll
;                     for (int e = 0; e < 2; ++e) { const float a = bf2f(yy[rr][k][e] & 0xffffu), b = bf2f(yy[rr][k][e] >> 16); s += a * a + b * b; }
;                 rstd[rr] = 1.0f / sqrtf(wave_sum(s) * (1.f / DM) + RMS_EPS); }
.LBB0_225:
	v_lshl_add_u64 v[98:99], s[64:65], 0, v[146:147]
	v_add_co_u32_e32 v66, vcc, 0x1000, v98
	v_lshl_add_u64 v[100:101], v[150:151], 0, s[46:47]
	s_nop 0
	v_addc_co_u32_e32 v67, vcc, 0, v99, vcc
	v_add_co_u32_e32 v114, vcc, 0x8800000, v100
	global_load_dwordx4 v[94:97], v[98:99], off
	global_load_dwordx4 v[90:93], v[98:99], off offset:1024
	global_load_dwordx4 v[86:89], v[98:99], off offset:2048
	global_load_dwordx4 v[82:85], v[98:99], off offset:3072
	v_addc_co_u32_e32 v115, vcc, 0, v101, vcc
	global_load_dwordx4 v[78:81], v[66:67], off
	global_load_dwordx4 v[74:77], v[66:67], off offset:1024
	global_load_dwordx4 v[70:73], v[66:67], off offset:2048
	s_nop 0
	global_load_dwordx4 v[66:69], v[66:67], off offset:3072
	v_add_co_u32_e32 v118, vcc, 0x9000000, v100
	global_load_dwordx2 v[116:117], v[114:115], off
	s_nop 0
	v_addc_co_u32_e32 v119, vcc, 0, v101, vcc
	global_load_dwordx2 v[120:121], v[118:119], off
	v_add_co_u32_e32 v122, vcc, 0x9800000, v100
	s_add_i32 s42, s42, s18
	s_nop 0
	v_addc_co_u32_e32 v123, vcc, 0, v101, vcc
	global_load_dwordx2 v[124:125], v[122:123], off
	v_add_co_u32_e32 v126, vcc, 0xa000000, v100
	v_lshl_add_u64 v[150:151], v[150:151], 0, s[22:23]
	s_nop 0
	v_addc_co_u32_e32 v127, vcc, 0, v101, vcc
	global_load_dwordx2 v[128:129], v[126:127], off
	v_add_co_u32_e32 v152, vcc, 0xa800000, v100
	s_waitcnt vmcnt(3)
	v_lshlrev_b32_e32 v168, 16, v116
	v_addc_co_u32_e32 v153, vcc, 0, v101, vcc
	global_load_dwordx2 v[154:155], v[152:153], off
	v_add_co_u32_e32 v156, vcc, 0xb000000, v100
	v_and_b32_e32 v169, 0xffff0000, v116
	s_nop 0
	v_addc_co_u32_e32 v157, vcc, 0, v101, vcc
	global_load_dwordx2 v[158:159], v[156:157], off
	v_add_co_u32_e32 v160, vcc, 0xb800000, v100
	v_lshlrev_b32_e32 v116, 16, v117
	s_nop 0
	v_addc_co_u32_e32 v161, vcc, 0, v101, vcc
	global_load_dwordx2 v[162:163], v[160:161], off
	v_add_co_u32_e32 v164, vcc, 0xc000000, v100
	v_and_b32_e32 v117, 0xffff0000, v117
	s_nop 0
	v_addc_co_u32_e32 v165, vcc, 0, v101, vcc
	global_load_dwordx2 v[166:167], v[164:165], off
	v_add_co_u32_e32 v100, vcc, s31, v98
	v_mul_f32_e32 v1, v169, v169
	s_nop 0
	v_addc_co_u32_e32 v101, vcc, 0, v99, vcc
	v_add_co_u32_e32 v130, vcc, s33, v98
	v_mul_f32_e32 v170, v117, v117
	s_nop 0
	v_addc_co_u32_e32 v131, vcc, 0, v99, vcc
	global_load_dwordx4 v[110:113], v[130:131], off offset:-4096
	global_load_dwordx4 v[106:109], v[100:101], off offset:1024
	global_load_dwordx4 v[102:105], v[100:101], off offset:2048
	s_nop 0
	global_load_dwordx4 v[98:101], v[100:101], off offset:3072
	s_nop 0
	global_load_dwordx4 v[142:145], v[130:131], off
	global_load_dwordx4 v[138:141], v[130:131], off offset:1024
	global_load_dwordx4 v[134:137], v[130:131], off offset:2048
	s_nop 0
	global_load_dwordx4 v[130:133], v[130:131], off offset:3072
	s_nop 0
	global_load_dwordx2 v[114:115], v[114:115], off offset:512
	s_nop 0
	global_load_dwordx2 v[118:119], v[118:119], off offset:512
	s_nop 0
	global_load_dwordx2 v[122:123], v[122:123], off offset:512
	s_nop 0
	global_load_dwordx2 v[126:127], v[126:127], off offset:512
	s_nop 0
	global_load_dwordx2 v[152:153], v[152:153], off offset:512
	s_nop 0
	global_load_dwordx2 v[156:157], v[156:157], off offset:512
	s_nop 0
	global_load_dwordx2 v[160:161], v[160:161], off offset:512
	s_nop 0
	global_load_dwordx2 v[164:165], v[164:165], off offset:512
	v_fmac_f32_e32 v1, v168, v168
	v_fmac_f32_e32 v170, v116, v116
	s_waitcnt vmcnt(22)
	v_and_b32_e32 v171, 0xffff0000, v120
	v_add_f32_e32 v1, v1, v170
	v_lshlrev_b32_e32 v170, 16, v120
	v_mul_f32_e32 v120, v171, v171
	v_fmac_f32_e32 v120, v170, v170
	v_add_f32_e32 v1, v1, v120
	v_lshlrev_b32_e32 v120, 16, v121
	v_and_b32_e32 v121, 0xffff0000, v121
	v_mul_f32_e32 v172, v121, v121
	v_fmac_f32_e32 v172, v120, v120
	s_waitcnt vmcnt(21)
	v_and_b32_e32 v173, 0xffff0000, v124
	v_add_f32_e32 v1, v172, v1
	v_lshlrev_b32_e32 v172, 16, v124
	v_mul_f32_e32 v124, v173, v173
	v_fmac_f32_e32 v124, v172, v172
	v_and_b32_e32 v175, 0xffff0000, v125
	v_add_f32_e32 v1, v124, v1
	v_lshlrev_b32_e32 v174, 16, v125
	v_mul_f32_e32 v124, v175, v175
	v_fmac_f32_e32 v124, v174, v174
	s_waitcnt vmcnt(20)
	v_and_b32_e32 v177, 0xffff0000, v128
	v_add_f32_e32 v1, v124, v1
	v_lshlrev_b32_e32 v176, 16, v128
	v_mul_f32_e32 v124, v177, v177
	v_fmac_f32_e32 v124, v176, v176
	v_and_b32_e32 v179, 0xffff0000, v129
	v_add_f32_e32 v1, v124, v1
	v_lshlrev_b32_e32 v178, 16, v129
	v_mul_f32_e32 v124, v179, v179
	v_fmac_f32_e32 v124, v178, v178
	v_add_f32_e32 v1, v124, v1
	s_waitcnt vmcnt(19)
	v_and_b32_e32 v181, 0xffff0000, v154
	v_lshlrev_b32_e32 v180, 16, v154
	v_mul_f32_e32 v124, v181, v181
	v_fmac_f32_e32 v124, v180, v180
	v_lshlrev_b32_e32 v154, 16, v155
	v_and_b32_e32 v155, 0xffff0000, v155
	v_add_f32_e32 v1, v124, v1
	v_mul_f32_e32 v124, v155, v155
	v_fmac_f32_e32 v124, v154, v154
	s_waitcnt vmcnt(18)
	v_and_b32_e32 v183, 0xffff0000, v158
	v_add_f32_e32 v1, v124, v1
	v_lshlrev_b32_e32 v182, 16, v158
	v_mul_f32_e32 v124, v183, v183
	v_fmac_f32_e32 v124, v182, v182
	v_lshlrev_b32_e32 v158, 16, v159
	v_and_b32_e32 v159, 0xffff0000, v159
	v_add_f32_e32 v1, v124, v1
	v_mul_f32_e32 v124, v159, v159
	v_fmac_f32_e32 v124, v158, v158
	s_waitcnt vmcnt(17)
	v_and_b32_e32 v185, 0xffff0000, v162
	v_add_f32_e32 v1, v124, v1
	v_lshlrev_b32_e32 v184, 16, v162
	v_mul_f32_e32 v124, v185, v185
	v_fmac_f32_e32 v124, v184, v184
	v_lshlrev_b32_e32 v162, 16, v163
	v_and_b32_e32 v163, 0xffff0000, v163
	v_add_f32_e32 v1, v124, v1
	v_mul_f32_e32 v124, v163, v163
	v_fmac_f32_e32 v124, v162, v162
	s_waitcnt vmcnt(16)
; __device__ __forceinline__ float bf2f(unsigned h) { return __uint_as_float(h << 16); }
; template <int MODE> ...
;     ...
;             for (int rr = 0; rr < RPW; ++rr) { float s = 0.f;
; #pragma unroll
;                 for (int k = 0; k < 8; ++k)
; #pragma unroll
;                     for (int e = 0; e < 2; ++e) { const float a = bf2f(yy[rr][k][e] & 0xffffu), b = bf2f(yy[rr][k][e] >> 16); s += a * a + b * b; }
;                 rstd[rr] = 1.0f / sqrtf(wave_sum(s) * (1.f / DM) + RMS_EPS); }
	v_and_b32_e32 v187, 0xffff0000, v166
	v_add_f32_e32 v1, v124, v1
	v_lshlrev_b32_e32 v186, 16, v166
	v_mul_f32_e32 v124, v187, v187
	v_fmac_f32_e32 v124, v186, v186
	v_lshlrev_b32_e32 v166, 16, v167
	v_and_b32_e32 v167, 0xffff0000, v167
	v_add_f32_e32 v1, v124, v1
	v_mul_f32_e32 v124, v167, v167
	v_fmac_f32_e32 v124, v166, v166
	v_add_f32_e32 v1, v124, v1
	s_waitcnt vmcnt(6)
	v_and_b32_e32 v191, 0xffff0000, v118
	v_lshlrev_b32_e32 v190, 16, v118
	v_add_f32_dpp v1, v1, v1 quad_perm:[1,0,3,2] row_mask:0xf bank_mask:0xf bound_ctrl:1
	v_mul_f32_e32 v118, v191, v191
	v_fmac_f32_e32 v118, v190, v190
	v_add_f32_dpp v1, v1, v1 quad_perm:[2,3,0,1] row_mask:0xf bank_mask:0xf bound_ctrl:1
	v_and_b32_e32 v193, 0xffff0000, v119
	v_lshlrev_b32_e32 v192, 16, v119
	v_add_f32_dpp v1, v1, v1 row_half_mirror row_mask:0xf bank_mask:0xf bound_ctrl:1
	s_waitcnt vmcnt(5)
	v_and_b32_e32 v195, 0xffff0000, v122
	v_lshlrev_b32_e32 v194, 16, v122
	v_add_f32_dpp v1, v1, v1 row_mirror row_mask:0xf bank_mask:0xf bound_ctrl:1
	v_mov_b32_e32 v124, v1
	s_nop 1
	v_permlane16_swap_b32_e32 v1, v124
	v_add_f32_e32 v1, v1, v124
	v_mov_b32_e32 v124, v1
	s_nop 1
	v_permlane32_swap_b32_e32 v1, v124
	v_add_f32_e32 v1, v1, v124
	v_fmamk_f32 v1, v1, 0x3a000000, v218
	v_cmp_gt_f32_e32 vcc, s30, v1
	v_mul_f32_e32 v124, 0x4f800000, v1
	v_and_b32_e32 v197, 0xffff0000, v123
	v_cndmask_b32_e32 v1, v1, v124, vcc
	v_sqrt_f32_e32 v124, v1
	v_lshlrev_b32_e32 v196, 16, v123
	s_waitcnt vmcnt(4)
	v_and_b32_e32 v199, 0xffff0000, v126
	v_lshlrev_b32_e32 v198, 16, v126
	v_add_u32_e32 v125, -1, v124
	v_fma_f32 v128, -v125, v124, v1
	v_cmp_ge_f32_e64 s[40:41], 0, v128
	v_add_u32_e32 v128, 1, v124
	v_and_b32_e32 v201, 0xffff0000, v127
	v_cndmask_b32_e64 v125, v124, v125, s[40:41]
	v_fma_f32 v124, -v128, v124, v1
	v_cmp_lt_f32_e64 s[40:41], 0, v124
	v_lshlrev_b32_e32 v200, 16, v127
	s_waitcnt vmcnt(3)
	v_and_b32_e32 v203, 0xffff0000, v152
	v_cndmask_b32_e64 v124, v125, v128, s[40:41]
	v_mul_f32_e32 v125, 0x37800000, v124
	v_cndmask_b32_e32 v124, v124, v125, vcc
	v_cmp_class_f32_e32 vcc, v1, v215
	v_lshlrev_b32_e32 v202, 16, v152
	v_lshlrev_b32_e32 v152, 16, v153
	v_cndmask_b32_e32 v1, v124, v1, vcc
	v_div_scale_f32 v124, s[0:1], v1, v1, 1.0
	v_rcp_f32_e32 v125, v124
	v_and_b32_e32 v153, 0xffff0000, v153
	s_waitcnt vmcnt(2)
	v_and_b32_e32 v205, 0xffff0000, v156
	v_lshlrev_b32_e32 v204, 16, v156
	v_fma_f32 v128, -v124, v125, 1.0
	v_fmac_f32_e32 v125, v128, v125
	v_div_scale_f32 v128, vcc, 1.0, v1, 1.0
	v_mul_f32_e32 v129, v128, v125
	v_fma_f32 v188, -v124, v129, v128
	v_fmac_f32_e32 v129, v188, v125
	v_fma_f32 v124, -v124, v129, v128
	v_div_fmas_f32 v124, v124, v125, v129
	v_div_fixup_f32 v188, v124, v1, 1.0
	v_lshlrev_b32_e32 v124, 16, v114
	v_and_b32_e32 v125, 0xffff0000, v114
	v_lshlrev_b32_e32 v114, 16, v115
	v_and_b32_e32 v115, 0xffff0000, v115
	v_mul_f32_e32 v1, v125, v125
	v_mul_f32_e32 v128, v115, v115
	v_fmac_f32_e32 v1, v124, v124
	v_fmac_f32_e32 v128, v114, v114
	v_add_f32_e32 v1, v1, v128
	v_add_f32_e32 v1, v1, v118
	v_mul_f32_e32 v118, v193, v193
	v_fmac_f32_e32 v118, v192, v192
	v_add_f32_e32 v1, v118, v1
	v_mul_f32_e32 v118, v195, v195
	v_fmac_f32_e32 v118, v194, v194
	v_add_f32_e32 v1, v118, v1
	v_mul_f32_e32 v118, v197, v197
	v_fmac_f32_e32 v118, v196, v196
	v_add_f32_e32 v1, v118, v1
	v_mul_f32_e32 v118, v199, v199
	v_fmac_f32_e32 v118, v198, v198
	v_add_f32_e32 v1, v118, v1
	v_mul_f32_e32 v118, v201, v201
	v_fmac_f32_e32 v118, v200, v200
	v_add_f32_e32 v1, v118, v1
	v_mul_f32_e32 v118, v203, v203
	v_fmac_f32_e32 v118, v202, v202
	v_add_f32_e32 v1, v118, v1
	v_mul_f32_e32 v118, v153, v153
	v_fmac_f32_e32 v118, v152, v152
	v_add_f32_e32 v1, v118, v1
	v_mul_f32_e32 v118, v205, v205
	v_fmac_f32_e32 v118, v204, v204
	v_lshlrev_b32_e32 v156, 16, v157
	v_and_b32_e32 v157, 0xffff0000, v157
	v_add_f32_e32 v1, v118, v1
	v_mul_f32_e32 v118, v157, v157
	v_fmac_f32_e32 v118, v156, v156
	s_waitcnt vmcnt(1)
	v_and_b32_e32 v207, 0xffff0000, v160
	v_add_f32_e32 v1, v118, v1
	v_lshlrev_b32_e32 v206, 16, v160
	v_mul_f32_e32 v118, v207, v207
	v_fmac_f32_e32 v118, v206, v206
	v_lshlrev_b32_e32 v160, 16, v161
	v_and_b32_e32 v161, 0xffff0000, v161
	v_add_f32_e32 v1, v118, v1
	v_mul_f32_e32 v118, v161, v161
	v_fmac_f32_e32 v118, v160, v160
	s_waitcnt vmcnt(0)
; __device__ __forceinline__ float bf2f(unsigned h) { return __uint_as_float(h << 16); }
; template <int MODE> ...
;     ...
;             for (int rr = 0; rr < RPW; ++rr) { float s = 0.f;
; #pragma unroll
;                 for (int k = 0; k < 8; ++k)
; #pragma unroll
;                     for (int e = 0; e < 2; ++e) { const float a = bf2f(yy[rr][k][e] & 0xffffu), b = bf2f(yy[rr][k][e] >> 16); s += a * a + b * b; }
;                 rstd[rr] = 1.0f / sqrtf(wave_sum(s) * (1.f / DM) + RMS_EPS); }
; #pragma unroll
;             for (int k = 0; k < 8; ++k) { const f32x4 g = *(const f32x4*)(gpost + k * 256 + lane * 4);
; #pragma unroll
;                 for (int rr = 0; rr < RPW; ++rr) { f32x4 yv;
;                     yv[0] = bf2f(yy[rr][k][0] & 0xffffu); yv[1] = bf2f(yy[rr][k][0] >> 16); yv[2] = bf2f(yy[rr][k][1] & 0xffffu); yv[3] = bf2f(yy[rr][k][1] >> 16);
;                     xv[rr][k] += yv * rstd[rr] * g; } }
	v_and_b32_e32 v209, 0xffff0000, v164
	v_add_f32_e32 v1, v118, v1
	v_lshlrev_b32_e32 v208, 16, v164
	v_mul_f32_e32 v118, v209, v209
	v_fmac_f32_e32 v118, v208, v208
	v_lshlrev_b32_e32 v164, 16, v165
	v_and_b32_e32 v165, 0xffff0000, v165
	v_add_f32_e32 v1, v118, v1
	v_mul_f32_e32 v118, v165, v165
	v_fmac_f32_e32 v118, v164, v164
	v_add_f32_e32 v1, v118, v1
	v_pk_mul_f32 v[116:117], v[188:189], v[116:117] op_sel_hi:[0,1]
	v_pk_fma_f32 v[128:129], v[4:5], v[116:117], v[96:97]
	v_add_f32_dpp v1, v1, v1 quad_perm:[1,0,3,2] row_mask:0xf bank_mask:0xf bound_ctrl:1
	s_nop 1
	v_add_f32_dpp v1, v1, v1 quad_perm:[2,3,0,1] row_mask:0xf bank_mask:0xf bound_ctrl:1
	s_nop 1
	v_add_f32_dpp v1, v1, v1 row_half_mirror row_mask:0xf bank_mask:0xf bound_ctrl:1
	s_nop 1
	v_add_f32_dpp v1, v1, v1 row_mirror row_mask:0xf bank_mask:0xf bound_ctrl:1
	v_mov_b32_e32 v118, v1
	s_nop 1
	v_permlane16_swap_b32_e32 v1, v118
	v_add_f32_e32 v1, v1, v118
	v_mov_b32_e32 v118, v1
	s_nop 1
	v_permlane32_swap_b32_e32 v1, v118
	v_add_f32_e32 v1, v1, v118
	v_fmamk_f32 v1, v1, 0x3a000000, v218
	v_cmp_gt_f32_e32 vcc, s30, v1
	v_mul_f32_e32 v118, 0x4f800000, v1
	s_nop 0
	v_cndmask_b32_e32 v1, v1, v118, vcc
	v_sqrt_f32_e32 v118, v1
	s_nop 0
	v_add_u32_e32 v119, -1, v118
	v_fma_f32 v122, -v119, v118, v1
	v_cmp_ge_f32_e64 s[40:41], 0, v122
	v_add_u32_e32 v122, 1, v118
	s_nop 0
	v_cndmask_b32_e64 v119, v118, v119, s[40:41]
	v_fma_f32 v118, -v122, v118, v1
	v_cmp_lt_f32_e64 s[40:41], 0, v118
	s_nop 1
	v_cndmask_b32_e64 v118, v119, v122, s[40:41]
	v_mul_f32_e32 v119, 0x37800000, v118
	v_cndmask_b32_e32 v118, v118, v119, vcc
	v_cmp_class_f32_e32 vcc, v1, v215
	s_nop 1
	v_cndmask_b32_e32 v1, v118, v1, vcc
	v_div_scale_f32 v118, s[0:1], v1, v1, 1.0
	v_rcp_f32_e32 v119, v118
	s_nop 0
	v_fma_f32 v122, -v118, v119, 1.0
	v_fmac_f32_e32 v119, v122, v119
	v_div_scale_f32 v122, vcc, 1.0, v1, 1.0
	v_mul_f32_e32 v123, v122, v119
	v_fma_f32 v126, -v118, v123, v122
	v_fmac_f32_e32 v123, v126, v119
	v_fma_f32 v118, -v118, v123, v122
	v_div_fmas_f32 v118, v118, v119, v123
	v_div_fixup_f32 v210, v118, v1, 1.0
	v_pk_mul_f32 v[118:119], v[188:189], v[168:169] op_sel_hi:[0,1]
	v_pk_fma_f32 v[126:127], v[2:3], v[118:119], v[94:95]
	v_pk_mul_f32 v[94:95], v[210:211], v[124:125] op_sel_hi:[0,1]
	v_pk_mul_f32 v[96:97], v[210:211], v[114:115] op_sel_hi:[0,1]
	v_pk_fma_f32 v[122:123], v[2:3], v[94:95], v[110:111]
	v_pk_mul_f32 v[94:95], v[188:189], v[170:171] op_sel_hi:[0,1]
	v_pk_fma_f32 v[124:125], v[4:5], v[96:97], v[112:113]
	v_pk_mul_f32 v[96:97], v[188:189], v[120:121] op_sel_hi:[0,1]
	v_pk_fma_f32 v[118:119], v[6:7], v[94:95], v[90:91]
	v_pk_mul_f32 v[90:91], v[210:211], v[190:191] op_sel_hi:[0,1]
	v_pk_fma_f32 v[120:121], v[8:9], v[96:97], v[92:93]
	v_pk_mul_f32 v[92:93], v[210:211], v[192:193] op_sel_hi:[0,1]
	v_pk_fma_f32 v[114:115], v[6:7], v[90:91], v[106:107]
	v_pk_mul_f32 v[90:91], v[188:189], v[172:173] op_sel_hi:[0,1]
	v_pk_fma_f32 v[116:117], v[8:9], v[92:93], v[108:109]
	v_pk_mul_f32 v[92:93], v[188:189], v[174:175] op_sel_hi:[0,1]
	v_pk_fma_f32 v[110:111], v[10:11], v[90:91], v[86:87]
	v_pk_mul_f32 v[86:87], v[210:211], v[194:195] op_sel_hi:[0,1]
	v_pk_fma_f32 v[112:113], v[12:13], v[92:93], v[88:89]
	v_pk_mul_f32 v[88:89], v[210:211], v[196:197] op_sel_hi:[0,1]
	v_pk_fma_f32 v[106:107], v[10:11], v[86:87], v[102:103]
	v_pk_mul_f32 v[86:87], v[188:189], v[176:177] op_sel_hi:[0,1]
	v_pk_fma_f32 v[108:109], v[12:13], v[88:89], v[104:105]
	v_pk_mul_f32 v[88:89], v[188:189], v[178:179] op_sel_hi:[0,1]
	v_pk_fma_f32 v[102:103], v[14:15], v[86:87], v[82:83]
	v_pk_mul_f32 v[82:83], v[210:211], v[198:199] op_sel_hi:[0,1]
	v_pk_fma_f32 v[104:105], v[16:17], v[88:89], v[84:85]
	v_pk_mul_f32 v[84:85], v[210:211], v[200:201] op_sel_hi:[0,1]
	v_pk_fma_f32 v[98:99], v[14:15], v[82:83], v[98:99]
	v_pk_mul_f32 v[82:83], v[188:189], v[180:181] op_sel_hi:[0,1]
	v_pk_fma_f32 v[100:101], v[16:17], v[84:85], v[100:101]
	v_pk_mul_f32 v[84:85], v[188:189], v[154:155] op_sel_hi:[0,1]
	v_pk_fma_f32 v[94:95], v[18:19], v[82:83], v[78:79]
	v_pk_mul_f32 v[78:79], v[210:211], v[202:203] op_sel_hi:[0,1]
	v_pk_fma_f32 v[96:97], v[20:21], v[84:85], v[80:81]
	v_pk_mul_f32 v[80:81], v[210:211], v[152:153] op_sel_hi:[0,1]
	v_pk_fma_f32 v[90:91], v[18:19], v[78:79], v[142:143]
	v_pk_mul_f32 v[78:79], v[188:189], v[182:183] op_sel_hi:[0,1]
	v_pk_fma_f32 v[92:93], v[20:21], v[80:81], v[144:145]
	v_pk_mul_f32 v[80:81], v[188:189], v[158:159] op_sel_hi:[0,1]
	v_pk_fma_f32 v[86:87], v[22:23], v[78:79], v[74:75]
	v_pk_mul_f32 v[74:75], v[210:211], v[204:205] op_sel_hi:[0,1]
	v_pk_fma_f32 v[88:89], v[24:25], v[80:81], v[76:77]
	v_pk_mul_f32 v[76:77], v[210:211], v[156:157] op_sel_hi:[0,1]
	v_pk_fma_f32 v[82:83], v[22:23], v[74:75], v[138:139]
	v_pk_mul_f32 v[74:75], v[188:189], v[184:185] op_sel_hi:[0,1]
	v_pk_fma_f32 v[84:85], v[24:25], v[76:77], v[140:141]
	v_pk_mul_f32 v[76:77], v[188:189], v[162:163] op_sel_hi:[0,1]
	v_pk_fma_f32 v[78:79], v[26:27], v[74:75], v[70:71]
	v_pk_mul_f32 v[70:71], v[210:211], v[206:207] op_sel_hi:[0,1]
	v_pk_fma_f32 v[80:81], v[28:29], v[76:77], v[72:73]
	v_pk_mul_f32 v[72:73], v[210:211], v[160:161] op_sel_hi:[0,1]
	v_pk_fma_f32 v[74:75], v[26:27], v[70:71], v[134:135]
	v_pk_mul_f32 v[70:71], v[188:189], v[186:187] op_sel_hi:[0,1]
	v_pk_fma_f32 v[76:77], v[28:29], v[72:73], v[136:137]
	v_pk_mul_f32 v[72:73], v[188:189], v[166:167] op_sel_hi:[0,1]
	v_pk_fma_f32 v[70:71], v[30:31], v[70:71], v[66:67]
	v_pk_mul_f32 v[66:67], v[210:211], v[208:209] op_sel_hi:[0,1]
	v_pk_fma_f32 v[72:73], v[32:33], v[72:73], v[68:69]
	v_pk_mul_f32 v[68:69], v[210:211], v[164:165] op_sel_hi:[0,1]
; template <int MODE> ...
;     ...
;         if (MODE != 0)
; #pragma unroll
;         for (int rr = 0; rr < RPW; ++rr) { float* xo = xres + (size_t)(m + rr) * DM + lane * 4;
; #pragma unroll
;             for (int k = 0; k < 8; ++k) *(f32x4*)(xo + k * 256) = xv[rr][k]; }
;         if (MODE <= 1) {
;             float rstd[RPW];
; #pragma unroll
;             for (int rr = 0; rr < RPW; ++rr) { float s = 0.f;
; #pragma unroll
;                 for (int k = 0; k < 8; ++k) s += (xv[rr][k][0] * xv[rr][k][0] + xv[rr][k][1] * xv[rr][k][1]) + (xv[rr][k][2] * xv[rr][k][2] + xv[rr][k][3] * xv[rr][k][3]);
;                 rstd[rr] = 1.0f / sqrtf(wave_sum(s) * (1.f / DM) + RMS_EPS); }
	v_pk_fma_f32 v[66:67], v[30:31], v[66:67], v[130:131]
	v_lshl_add_u64 v[130:131], s[78:79], 0, v[146:147]
	v_pk_fma_f32 v[68:69], v[32:33], v[68:69], v[132:133]
	v_add_co_u32_e32 v132, vcc, s19, v130
	global_store_dwordx4 v[130:131], v[126:129], off sc0 sc1
	global_store_dwordx4 v[130:131], v[118:121], off offset:1024 sc0 sc1
	global_store_dwordx4 v[130:131], v[110:113], off offset:2048 sc0 sc1
	global_store_dwordx4 v[130:131], v[102:105], off offset:3072 sc0 sc1
	v_addc_co_u32_e32 v133, vcc, 0, v131, vcc
	v_add_co_u32_e32 v134, vcc, s31, v130
	v_mul_f32_e32 v1, v127, v127
	s_nop 0
	v_addc_co_u32_e32 v135, vcc, 0, v131, vcc
	v_add_co_u32_e32 v130, vcc, s33, v130
	global_store_dwordx4 v[134:135], v[94:97], off offset:-4096 sc0 sc1
	global_store_dwordx4 v[132:133], v[86:89], off offset:1024 sc0 sc1
	global_store_dwordx4 v[132:133], v[78:81], off offset:2048 sc0 sc1
	global_store_dwordx4 v[132:133], v[70:73], off offset:3072 sc0 sc1
	global_store_dwordx4 v[134:135], v[122:125], off sc0 sc1
	global_store_dwordx4 v[134:135], v[114:117], off offset:1024 sc0 sc1
	global_store_dwordx4 v[134:135], v[106:109], off offset:2048 sc0 sc1
	global_store_dwordx4 v[134:135], v[98:101], off offset:3072 sc0 sc1
	v_addc_co_u32_e32 v131, vcc, 0, v131, vcc
	global_store_dwordx4 v[130:131], v[90:93], off sc0 sc1
	global_store_dwordx4 v[130:131], v[82:85], off offset:1024 sc0 sc1
	global_store_dwordx4 v[130:131], v[74:77], off offset:2048 sc0 sc1
	global_store_dwordx4 v[130:131], v[66:69], off offset:3072 sc0 sc1
	v_mul_f32_e32 v130, v129, v129
	v_fmac_f32_e32 v1, v126, v126
	v_fmac_f32_e32 v130, v128, v128
	v_add_f32_e32 v1, v1, v130
	v_mul_f32_e32 v130, v119, v119
	v_mul_f32_e32 v131, v121, v121
	v_fmac_f32_e32 v130, v118, v118
	v_fmac_f32_e32 v131, v120, v120
	v_add_f32_e32 v130, v130, v131
	v_add_f32_e32 v1, v1, v130
	v_mul_f32_e32 v130, v111, v111
	v_mul_f32_e32 v131, v113, v113
	v_fmac_f32_e32 v130, v110, v110
	v_fmac_f32_e32 v131, v112, v112
	v_add_f32_e32 v130, v130, v131
	v_add_f32_e32 v1, v130, v1
	v_mul_f32_e32 v130, v103, v103
	v_mul_f32_e32 v131, v105, v105
	v_fmac_f32_e32 v130, v102, v102
	v_fmac_f32_e32 v131, v104, v104
	v_add_f32_e32 v130, v130, v131
	v_add_f32_e32 v1, v130, v1
	v_mul_f32_e32 v130, v95, v95
	v_mul_f32_e32 v131, v97, v97
	v_fmac_f32_e32 v130, v94, v94
	v_fmac_f32_e32 v131, v96, v96
	v_add_f32_e32 v130, v130, v131
	v_add_f32_e32 v1, v130, v1
	v_mul_f32_e32 v130, v87, v87
	v_mul_f32_e32 v131, v89, v89
	v_fmac_f32_e32 v130, v86, v86
	v_fmac_f32_e32 v131, v88, v88
	v_add_f32_e32 v130, v130, v131
	v_add_f32_e32 v1, v130, v1
	v_mul_f32_e32 v130, v79, v79
	v_mul_f32_e32 v131, v81, v81
	v_fmac_f32_e32 v130, v78, v78
	v_fmac_f32_e32 v131, v80, v80
	v_add_f32_e32 v130, v130, v131
	v_add_f32_e32 v1, v130, v1
	v_mul_f32_e32 v130, v71, v71
	v_mul_f32_e32 v131, v73, v73
	v_fmac_f32_e32 v130, v70, v70
	v_fmac_f32_e32 v131, v72, v72
	v_add_f32_e32 v130, v130, v131
	v_add_f32_e32 v1, v130, v1
	s_add_u32 s78, s78, s26
	s_addc_u32 s79, s79, s27
	v_add_f32_dpp v1, v1, v1 quad_perm:[1,0,3,2] row_mask:0xf bank_mask:0xf bound_ctrl:1
	s_add_u32 s64, s64, s26
	s_addc_u32 s65, s65, s27
	v_add_f32_dpp v1, v1, v1 quad_perm:[2,3,0,1] row_mask:0xf bank_mask:0xf bound_ctrl:1
	s_cmpk_gt_i32 s42, 0x3fff
	s_nop 0
	v_add_f32_dpp v1, v1, v1 row_half_mirror row_mask:0xf bank_mask:0xf bound_ctrl:1
	s_nop 1
	v_add_f32_dpp v1, v1, v1 row_mirror row_mask:0xf bank_mask:0xf bound_ctrl:1
	v_mov_b32_e32 v130, v1
	s_nop 1
	v_permlane16_swap_b32_e32 v1, v130
	v_add_f32_e32 v1, v1, v130
	v_mov_b32_e32 v130, v1
	s_nop 1
	v_permlane32_swap_b32_e32 v1, v130
	v_add_f32_e32 v1, v1, v130
	v_fmamk_f32 v1, v1, 0x3a000000, v218
	v_cmp_gt_f32_e32 vcc, s30, v1
	v_mul_f32_e32 v130, 0x4f800000, v1
	s_nop 0
	v_cndmask_b32_e32 v1, v1, v130, vcc
	v_sqrt_f32_e32 v130, v1
	s_nop 0
	v_add_u32_e32 v131, -1, v130
	v_fma_f32 v132, -v131, v130, v1
	v_cmp_ge_f32_e64 s[40:41], 0, v132
	v_add_u32_e32 v132, 1, v130
	s_nop 0
	v_cndmask_b32_e64 v131, v130, v131, s[40:41]
	v_fma_f32 v130, -v132, v130, v1
	v_cmp_lt_f32_e64 s[40:41], 0, v130
	s_nop 1
	v_cndmask_b32_e64 v130, v131, v132, s[40:41]
	v_mul_f32_e32 v131, 0x37800000, v130
	v_cndmask_b32_e32 v130, v130, v131, vcc
	v_cmp_class_f32_e32 vcc, v1, v215
	s_nop 1
	v_cndmask_b32_e32 v1, v130, v1, vcc
	v_div_scale_f32 v130, s[0:1], v1, v1, 1.0
	v_rcp_f32_e32 v131, v130
	s_nop 0
	v_fma_f32 v132, -v130, v131, 1.0
	v_fmac_f32_e32 v131, v132, v131
	v_div_scale_f32 v132, vcc, 1.0, v1, 1.0
	v_mul_f32_e32 v133, v132, v131
	v_fma_f32 v134, -v130, v133, v132
	v_fmac_f32_e32 v133, v134, v131
	v_fma_f32 v130, -v130, v133, v132
	v_div_fmas_f32 v130, v130, v131, v133
	v_div_fixup_f32 v130, v130, v1, 1.0
	v_mul_f32_e32 v1, v123, v123
	v_mul_f32_e32 v131, v125, v125
	v_fmac_f32_e32 v1, v122, v122
	v_fmac_f32_e32 v131, v124, v124
	v_add_f32_e32 v1, v1, v131
	v_mul_f32_e32 v131, v115, v115
	v_mul_f32_e32 v132, v117, v117
	v_fmac_f32_e32 v131, v114, v114
	v_fmac_f32_e32 v132, v116, v116
	v_add_f32_e32 v131, v131, v132
	v_add_f32_e32 v1, v1, v131
	v_mul_f32_e32 v131, v107, v107
	v_mul_f32_e32 v132, v109, v109
	v_fmac_f32_e32 v131, v106, v106
	v_fmac_f32_e32 v132, v108, v108
	v_add_f32_e32 v131, v131, v132
	v_add_f32_e32 v1, v131, v1
	v_mul_f32_e32 v131, v99, v99
	v_mul_f32_e32 v132, v101, v101
	v_fmac_f32_e32 v131, v98, v98
	v_fmac_f32_e32 v132, v100, v100
	v_add_f32_e32 v131, v131, v132
	v_add_f32_e32 v1, v131, v1
	v_mul_f32_e32 v131, v91, v91
	v_mul_f32_e32 v132, v93, v93
	v_fmac_f32_e32 v131, v90, v90
	v_fmac_f32_e32 v132, v92, v92
	v_add_f32_e32 v131, v131, v132
	v_add_f32_e32 v1, v131, v1
	v_mul_f32_e32 v131, v83, v83
	v_mul_f32_e32 v132, v85, v85
	v_fmac_f32_e32 v131, v82, v82
; __device__ __forceinline__ unsigned pk2(float lo, float hi) { return f2bf(lo) | (f2bf(hi) << 16); }
; template <int MODE> ...
;     ...
;             for (int rr = 0; rr < RPW; ++rr) { float s = 0.f;
; #pragma unroll
;                 for (int k = 0; k < 8; ++k) s += (xv[rr][k][0] * xv[rr][k][0] + xv[rr][k][1] * xv[rr][k][1]) + (xv[rr][k][2] * xv[rr][k][2] + xv[rr][k][3] * xv[rr][k][3]);
;                 rstd[rr] = 1.0f / sqrtf(wave_sum(s) * (1.f / DM) + RMS_EPS); }
; #pragma unroll
;             for (int k = 0; k < 8; ++k) { const f32x4 g = *(const f32x4*)(gpre + k * 256 + lane * 4);
; #pragma unroll
;                 for (int rr = 0; rr < RPW; ++rr) { const f32x4 a = xv[rr][k] * rstd[rr] * g;
;                     v2u o; o.x = pk2(a[0], a[1]); o.y = pk2(a[2], a[3]);
;                     *(v2u*)(h + ((size_t)(k * 4 + (lane >> 4)) * M_TOK + (m + rr)) * 64 + (lane & 15) * 4) = o; } }
	v_fmac_f32_e32 v132, v84, v84
	v_add_f32_e32 v131, v131, v132
	v_add_f32_e32 v1, v131, v1
	v_mul_f32_e32 v131, v75, v75
	v_mul_f32_e32 v132, v77, v77
	v_fmac_f32_e32 v131, v74, v74
	v_fmac_f32_e32 v132, v76, v76
	v_add_f32_e32 v131, v131, v132
	v_add_f32_e32 v1, v131, v1
	v_mul_f32_e32 v131, v67, v67
	v_mul_f32_e32 v132, v69, v69
	v_fmac_f32_e32 v131, v66, v66
	v_fmac_f32_e32 v132, v68, v68
	v_add_f32_e32 v131, v131, v132
	v_add_f32_e32 v1, v131, v1
	s_nop 1
	v_add_f32_dpp v1, v1, v1 quad_perm:[1,0,3,2] row_mask:0xf bank_mask:0xf bound_ctrl:1
	s_nop 1
	v_add_f32_dpp v1, v1, v1 quad_perm:[2,3,0,1] row_mask:0xf bank_mask:0xf bound_ctrl:1
	s_nop 1
	v_add_f32_dpp v1, v1, v1 row_half_mirror row_mask:0xf bank_mask:0xf bound_ctrl:1
	s_nop 1
	v_add_f32_dpp v1, v1, v1 row_mirror row_mask:0xf bank_mask:0xf bound_ctrl:1
	v_mov_b32_e32 v131, v1
	s_nop 1
	v_permlane16_swap_b32_e32 v1, v131
	v_add_f32_e32 v1, v1, v131
	v_mov_b32_e32 v131, v1
	s_nop 1
	v_permlane32_swap_b32_e32 v1, v131
	v_add_f32_e32 v1, v1, v131
	v_fmamk_f32 v1, v1, 0x3a000000, v218
	v_cmp_gt_f32_e32 vcc, s30, v1
	v_mul_f32_e32 v131, 0x4f800000, v1
	s_nop 0
	v_cndmask_b32_e32 v1, v1, v131, vcc
	v_sqrt_f32_e32 v131, v1
	s_nop 0
	v_add_u32_e32 v132, -1, v131
	v_fma_f32 v133, -v132, v131, v1
	v_cmp_ge_f32_e64 s[40:41], 0, v133
	v_add_u32_e32 v133, 1, v131
	s_nop 0
	v_cndmask_b32_e64 v132, v131, v132, s[40:41]
	v_fma_f32 v131, -v133, v131, v1
	v_cmp_lt_f32_e64 s[40:41], 0, v131
	s_nop 1
	v_cndmask_b32_e64 v131, v132, v133, s[40:41]
	v_mul_f32_e32 v132, 0x37800000, v131
	v_cndmask_b32_e32 v131, v131, v132, vcc
	v_cmp_class_f32_e32 vcc, v1, v215
	s_nop 1
	v_cndmask_b32_e32 v1, v131, v1, vcc
	v_div_scale_f32 v131, s[0:1], v1, v1, 1.0
	v_rcp_f32_e32 v132, v131
	s_mov_b32 s0, 0x4800000
	v_fma_f32 v133, -v131, v132, 1.0
	v_fmac_f32_e32 v132, v133, v132
	v_div_scale_f32 v133, vcc, 1.0, v1, 1.0
	v_mul_f32_e32 v134, v133, v132
	v_fma_f32 v135, -v131, v134, v133
	v_fmac_f32_e32 v134, v135, v132
	v_fma_f32 v131, -v131, v134, v133
	v_div_fmas_f32 v131, v131, v132, v134
	v_pk_mul_f32 v[126:127], v[126:127], v[130:131] op_sel_hi:[1,0]
	v_div_fixup_f32 v132, v131, v1, 1.0
	v_pk_mul_f32 v[126:127], v[46:47], v[126:127]
	v_pk_mul_f32 v[128:129], v[128:129], v[130:131] op_sel_hi:[1,0]
	v_bfe_u32 v1, v126, 16, 1
	v_add3_u32 v1, v126, v1, s63
	v_bfe_u32 v126, v127, 16, 1
	v_pk_mul_f32 v[128:129], v[48:49], v[128:129]
	v_lshrrev_b32_e32 v1, 16, v1
	v_add3_u32 v126, v127, v126, s63
	v_and_or_b32 v126, v126, s60, v1
	v_bfe_u32 v1, v128, 16, 1
	v_add3_u32 v1, v128, v1, s63
	v_bfe_u32 v127, v129, 16, 1
	v_pk_mul_f32 v[122:123], v[122:123], v[132:133] op_sel_hi:[1,0]
	v_lshrrev_b32_e32 v1, 16, v1
	v_add3_u32 v127, v129, v127, s63
	v_pk_mul_f32 v[122:123], v[46:47], v[122:123]
	v_and_or_b32 v127, v127, s60, v1
	v_bfe_u32 v1, v122, 16, 1
	v_pk_mul_f32 v[124:125], v[124:125], v[132:133] op_sel_hi:[1,0]
	v_add3_u32 v1, v122, v1, s63
	v_bfe_u32 v122, v123, 16, 1
	v_pk_mul_f32 v[124:125], v[48:49], v[124:125]
	v_lshrrev_b32_e32 v1, 16, v1
	v_add3_u32 v122, v123, v122, s63
	v_and_or_b32 v122, v122, s60, v1
	v_bfe_u32 v1, v124, 16, 1
	v_add3_u32 v1, v124, v1, s63
	v_bfe_u32 v123, v125, 16, 1
	v_pk_mul_f32 v[118:119], v[118:119], v[130:131] op_sel_hi:[1,0]
	v_lshrrev_b32_e32 v1, 16, v1
	v_add3_u32 v123, v125, v123, s63
	v_pk_mul_f32 v[118:119], v[34:35], v[118:119]
	v_and_or_b32 v123, v123, s60, v1
	v_bfe_u32 v1, v118, 16, 1
	v_pk_mul_f32 v[120:121], v[120:121], v[130:131] op_sel_hi:[1,0]
	v_add3_u32 v1, v118, v1, s63
	v_bfe_u32 v118, v119, 16, 1
	v_pk_mul_f32 v[120:121], v[36:37], v[120:121]
	v_lshrrev_b32_e32 v1, 16, v1
	v_add3_u32 v118, v119, v118, s63
	v_and_or_b32 v118, v118, s60, v1
	v_bfe_u32 v1, v120, 16, 1
	v_add3_u32 v1, v120, v1, s63
	v_bfe_u32 v119, v121, 16, 1
	v_pk_mul_f32 v[114:115], v[114:115], v[132:133] op_sel_hi:[1,0]
	v_lshrrev_b32_e32 v1, 16, v1
	v_add3_u32 v119, v121, v119, s63
	v_pk_mul_f32 v[114:115], v[34:35], v[114:115]
	v_and_or_b32 v119, v119, s60, v1
	v_bfe_u32 v1, v114, 16, 1
	v_pk_mul_f32 v[116:117], v[116:117], v[132:133] op_sel_hi:[1,0]
	v_add3_u32 v1, v114, v1, s63
	v_bfe_u32 v114, v115, 16, 1
	v_pk_mul_f32 v[116:117], v[36:37], v[116:117]
	v_lshrrev_b32_e32 v1, 16, v1
	v_add3_u32 v114, v115, v114, s63
	v_and_or_b32 v114, v114, s60, v1
	v_bfe_u32 v1, v116, 16, 1
	v_add3_u32 v1, v116, v1, s63
	v_bfe_u32 v115, v117, 16, 1
	v_pk_mul_f32 v[110:111], v[110:111], v[130:131] op_sel_hi:[1,0]
	v_lshrrev_b32_e32 v1, 16, v1
	v_add3_u32 v115, v117, v115, s63
	v_pk_mul_f32 v[110:111], v[38:39], v[110:111]
	v_and_or_b32 v115, v115, s60, v1
	v_bfe_u32 v1, v110, 16, 1
	v_pk_mul_f32 v[112:113], v[112:113], v[130:131] op_sel_hi:[1,0]
	v_add3_u32 v1, v110, v1, s63
	v_bfe_u32 v110, v111, 16, 1
	v_pk_mul_f32 v[112:113], v[40:41], v[112:113]
	v_lshrrev_b32_e32 v1, 16, v1
	v_add3_u32 v110, v111, v110, s63
	v_and_or_b32 v110, v110, s60, v1
	v_bfe_u32 v1, v112, 16, 1
	v_add3_u32 v1, v112, v1, s63
	v_bfe_u32 v111, v113, 16, 1
	v_pk_mul_f32 v[106:107], v[106:107], v[132:133] op_sel_hi:[1,0]
	v_lshrrev_b32_e32 v1, 16, v1
	v_add3_u32 v111, v113, v111, s63
	v_pk_mul_f32 v[106:107], v[38:39], v[106:107]
	v_and_or_b32 v111, v111, s60, v1
	v_bfe_u32 v1, v106, 16, 1
	v_pk_mul_f32 v[108:109], v[108:109], v[132:133] op_sel_hi:[1,0]
	v_add3_u32 v1, v106, v1, s63
	v_bfe_u32 v106, v107, 16, 1
	v_pk_mul_f32 v[108:109], v[40:41], v[108:109]
	v_lshrrev_b32_e32 v1, 16, v1
	v_add3_u32 v106, v107, v106, s63
	v_and_or_b32 v106, v106, s60, v1
	v_bfe_u32 v1, v108, 16, 1
	v_add3_u32 v1, v108, v1, s63
	v_bfe_u32 v107, v109, 16, 1
	v_pk_mul_f32 v[102:103], v[102:103], v[130:131] op_sel_hi:[1,0]
	v_lshrrev_b32_e32 v1, 16, v1
; __device__ __forceinline__ unsigned pk2(float lo, float hi) { return f2bf(lo) | (f2bf(hi) << 16); }
; template <int MODE> ...
;     ...
; #pragma unroll
;             for (int k = 0; k < 8; ++k) { const f32x4 g = *(const f32x4*)(gpre + k * 256 + lane * 4);
; #pragma unroll
;                 for (int rr = 0; rr < RPW; ++rr) { const f32x4 a = xv[rr][k] * rstd[rr] * g;
;                     v2u o; o.x = pk2(a[0], a[1]); o.y = pk2(a[2], a[3]);
;                     *(v2u*)(h + ((size_t)(k * 4 + (lane >> 4)) * M_TOK + (m + rr)) * 64 + (lane & 15) * 4) = o; } }
	v_add3_u32 v107, v109, v107, s63
	v_pk_mul_f32 v[102:103], v[42:43], v[102:103]
	v_and_or_b32 v107, v107, s60, v1
	v_bfe_u32 v1, v102, 16, 1
	v_pk_mul_f32 v[104:105], v[104:105], v[130:131] op_sel_hi:[1,0]
	v_add3_u32 v1, v102, v1, s63
	v_bfe_u32 v102, v103, 16, 1
	v_pk_mul_f32 v[104:105], v[44:45], v[104:105]
	v_lshrrev_b32_e32 v1, 16, v1
	v_add3_u32 v102, v103, v102, s63
	v_and_or_b32 v102, v102, s60, v1
	v_bfe_u32 v1, v104, 16, 1
	v_add3_u32 v1, v104, v1, s63
	v_bfe_u32 v103, v105, 16, 1
	v_pk_mul_f32 v[98:99], v[98:99], v[132:133] op_sel_hi:[1,0]
	v_lshrrev_b32_e32 v1, 16, v1
	v_add3_u32 v103, v105, v103, s63
	v_pk_mul_f32 v[98:99], v[42:43], v[98:99]
	v_and_or_b32 v103, v103, s60, v1
	v_bfe_u32 v1, v98, 16, 1
	v_pk_mul_f32 v[100:101], v[100:101], v[132:133] op_sel_hi:[1,0]
	v_add3_u32 v1, v98, v1, s63
	v_bfe_u32 v98, v99, 16, 1
	v_pk_mul_f32 v[100:101], v[44:45], v[100:101]
	v_lshrrev_b32_e32 v1, 16, v1
	v_add3_u32 v98, v99, v98, s63
	v_and_or_b32 v98, v98, s60, v1
	v_bfe_u32 v1, v100, 16, 1
	v_add3_u32 v1, v100, v1, s63
	v_bfe_u32 v99, v101, 16, 1
	v_pk_mul_f32 v[94:95], v[94:95], v[130:131] op_sel_hi:[1,0]
	v_lshrrev_b32_e32 v1, 16, v1
	v_add3_u32 v99, v101, v99, s63
	v_pk_mul_f32 v[94:95], v[50:51], v[94:95]
	v_and_or_b32 v99, v99, s60, v1
	v_bfe_u32 v1, v94, 16, 1
	v_pk_mul_f32 v[96:97], v[96:97], v[130:131] op_sel_hi:[1,0]
	v_add3_u32 v1, v94, v1, s63
	v_bfe_u32 v94, v95, 16, 1
	v_pk_mul_f32 v[96:97], v[52:53], v[96:97]
	v_lshrrev_b32_e32 v1, 16, v1
	v_add3_u32 v94, v95, v94, s63
	v_and_or_b32 v94, v94, s60, v1
	v_bfe_u32 v1, v96, 16, 1
	v_add3_u32 v1, v96, v1, s63
	v_bfe_u32 v95, v97, 16, 1
	v_pk_mul_f32 v[90:91], v[90:91], v[132:133] op_sel_hi:[1,0]
	v_lshrrev_b32_e32 v1, 16, v1
	v_add3_u32 v95, v97, v95, s63
	v_pk_mul_f32 v[90:91], v[50:51], v[90:91]
	v_and_or_b32 v95, v95, s60, v1
	v_bfe_u32 v1, v90, 16, 1
	v_pk_mul_f32 v[92:93], v[92:93], v[132:133] op_sel_hi:[1,0]
	v_add3_u32 v1, v90, v1, s63
	v_bfe_u32 v90, v91, 16, 1
	v_pk_mul_f32 v[92:93], v[52:53], v[92:93]
	v_lshrrev_b32_e32 v1, 16, v1
	v_add3_u32 v90, v91, v90, s63
	v_and_or_b32 v90, v90, s60, v1
	v_bfe_u32 v1, v92, 16, 1
	v_add3_u32 v1, v92, v1, s63
	v_bfe_u32 v91, v93, 16, 1
	v_pk_mul_f32 v[86:87], v[86:87], v[130:131] op_sel_hi:[1,0]
	v_lshrrev_b32_e32 v1, 16, v1
	v_add3_u32 v91, v93, v91, s63
	v_pk_mul_f32 v[86:87], v[54:55], v[86:87]
	v_and_or_b32 v91, v91, s60, v1
	v_bfe_u32 v1, v86, 16, 1
	v_pk_mul_f32 v[88:89], v[88:89], v[130:131] op_sel_hi:[1,0]
	v_add3_u32 v1, v86, v1, s63
	v_bfe_u32 v86, v87, 16, 1
	v_pk_mul_f32 v[88:89], v[56:57], v[88:89]
	v_lshrrev_b32_e32 v1, 16, v1
	v_add3_u32 v86, v87, v86, s63
	v_and_or_b32 v86, v86, s60, v1
	v_bfe_u32 v1, v88, 16, 1
	v_add3_u32 v1, v88, v1, s63
	v_bfe_u32 v87, v89, 16, 1
	v_pk_mul_f32 v[82:83], v[82:83], v[132:133] op_sel_hi:[1,0]
	v_lshrrev_b32_e32 v1, 16, v1
	v_add3_u32 v87, v89, v87, s63
	v_pk_mul_f32 v[82:83], v[54:55], v[82:83]
	v_and_or_b32 v87, v87, s60, v1
	v_bfe_u32 v1, v82, 16, 1
	v_pk_mul_f32 v[84:85], v[84:85], v[132:133] op_sel_hi:[1,0]
	v_add3_u32 v1, v82, v1, s63
	v_bfe_u32 v82, v83, 16, 1
	v_pk_mul_f32 v[84:85], v[56:57], v[84:85]
	v_lshrrev_b32_e32 v1, 16, v1
	v_add3_u32 v82, v83, v82, s63
	v_and_or_b32 v82, v82, s60, v1
	v_bfe_u32 v1, v84, 16, 1
	v_add3_u32 v1, v84, v1, s63
	v_bfe_u32 v83, v85, 16, 1
	v_pk_mul_f32 v[78:79], v[78:79], v[130:131] op_sel_hi:[1,0]
	v_lshrrev_b32_e32 v1, 16, v1
	v_add3_u32 v83, v85, v83, s63
	v_pk_mul_f32 v[78:79], v[58:59], v[78:79]
	v_and_or_b32 v83, v83, s60, v1
	v_bfe_u32 v1, v78, 16, 1
	v_pk_mul_f32 v[80:81], v[80:81], v[130:131] op_sel_hi:[1,0]
	v_add3_u32 v1, v78, v1, s63
	v_bfe_u32 v78, v79, 16, 1
	v_pk_mul_f32 v[80:81], v[60:61], v[80:81]
	v_lshrrev_b32_e32 v1, 16, v1
	v_add3_u32 v78, v79, v78, s63
	v_and_or_b32 v78, v78, s60, v1
; __device__ __forceinline__ unsigned pk2(float lo, float hi) { return f2bf(lo) | (f2bf(hi) << 16); }
; template <int MODE> ...
;     for (int m = RPW * gw; m < M_TOK; m += RPW * NGW) {
;     ...
;             for (int k = 0; k < 8; ++k) { const f32x4 g = *(const f32x4*)(gpre + k * 256 + lane * 4);
; #pragma unroll
;                 for (int rr = 0; rr < RPW; ++rr) { const f32x4 a = xv[rr][k] * rstd[rr] * g;
;                     v2u o; o.x = pk2(a[0], a[1]); o.y = pk2(a[2], a[3]);
;                     *(v2u*)(h + ((size_t)(k * 4 + (lane >> 4)) * M_TOK + (m + rr)) * 64 + (lane & 15) * 4) = o; } }
	v_bfe_u32 v1, v80, 16, 1
	v_add3_u32 v1, v80, v1, s63
	v_bfe_u32 v79, v81, 16, 1
	v_pk_mul_f32 v[74:75], v[74:75], v[132:133] op_sel_hi:[1,0]
	v_lshrrev_b32_e32 v1, 16, v1
	v_add3_u32 v79, v81, v79, s63
	v_pk_mul_f32 v[74:75], v[58:59], v[74:75]
	v_and_or_b32 v79, v79, s60, v1
	v_bfe_u32 v1, v74, 16, 1
	v_pk_mul_f32 v[76:77], v[76:77], v[132:133] op_sel_hi:[1,0]
	v_add3_u32 v1, v74, v1, s63
	v_bfe_u32 v74, v75, 16, 1
	v_lshl_add_u64 v[128:129], v[148:149], 0, s[46:47]
	v_pk_mul_f32 v[76:77], v[60:61], v[76:77]
	v_lshrrev_b32_e32 v1, 16, v1
	v_add3_u32 v74, v75, v74, s63
	v_add_co_u32_e32 v134, vcc, s0, v128
	v_and_or_b32 v74, v74, s60, v1
	v_bfe_u32 v1, v76, 16, 1
	v_addc_co_u32_e32 v135, vcc, 0, v129, vcc
	s_mov_b32 s0, 0x5000000
	v_add3_u32 v1, v76, v1, s63
	v_bfe_u32 v75, v77, 16, 1
	v_pk_mul_f32 v[70:71], v[70:71], v[130:131] op_sel_hi:[1,0]
	v_add_co_u32_e32 v120, vcc, s0, v128
	v_lshrrev_b32_e32 v1, 16, v1
	v_add3_u32 v75, v77, v75, s63
	v_pk_mul_f32 v[70:71], v[62:63], v[70:71]
	v_addc_co_u32_e32 v121, vcc, 0, v129, vcc
	s_mov_b32 s0, 0x5800000
	v_and_or_b32 v75, v75, s60, v1
	v_bfe_u32 v1, v70, 16, 1
	v_add_co_u32_e32 v112, vcc, s0, v128
	v_pk_mul_f32 v[72:73], v[72:73], v[130:131] op_sel_hi:[1,0]
	v_add3_u32 v1, v70, v1, s63
	v_bfe_u32 v70, v71, 16, 1
	v_addc_co_u32_e32 v113, vcc, 0, v129, vcc
	s_mov_b32 s0, 0x6000000
	v_pk_mul_f32 v[72:73], v[64:65], v[72:73]
	v_lshrrev_b32_e32 v1, 16, v1
	v_add3_u32 v70, v71, v70, s63
	v_add_co_u32_e32 v104, vcc, s0, v128
	v_and_or_b32 v70, v70, s60, v1
	v_bfe_u32 v1, v72, 16, 1
	v_addc_co_u32_e32 v105, vcc, 0, v129, vcc
	s_mov_b32 s0, 0x6800000
	v_add3_u32 v1, v72, v1, s63
	v_bfe_u32 v71, v73, 16, 1
	v_pk_mul_f32 v[66:67], v[66:67], v[132:133] op_sel_hi:[1,0]
	v_add_co_u32_e32 v96, vcc, s0, v128
	v_lshrrev_b32_e32 v1, 16, v1
	v_add3_u32 v71, v73, v71, s63
	v_pk_mul_f32 v[66:67], v[62:63], v[66:67]
	v_addc_co_u32_e32 v97, vcc, 0, v129, vcc
	s_mov_b32 s0, 0x7000000
	v_and_or_b32 v71, v71, s60, v1
	v_bfe_u32 v1, v66, 16, 1
	v_add_co_u32_e32 v88, vcc, s0, v128
	v_pk_mul_f32 v[68:69], v[68:69], v[132:133] op_sel_hi:[1,0]
	v_add3_u32 v1, v66, v1, s63
	v_bfe_u32 v66, v67, 16, 1
	v_addc_co_u32_e32 v89, vcc, 0, v129, vcc
	s_mov_b32 s0, 0x7800000
	v_pk_mul_f32 v[68:69], v[64:65], v[68:69]
	v_lshrrev_b32_e32 v1, 16, v1
	v_add3_u32 v66, v67, v66, s63
	v_add_co_u32_e32 v80, vcc, s0, v128
	v_and_or_b32 v66, v66, s60, v1
	v_bfe_u32 v1, v68, 16, 1
	v_addc_co_u32_e32 v81, vcc, 0, v129, vcc
	s_brev_b32 s0, 16
	v_add3_u32 v1, v68, v1, s63
	v_bfe_u32 v67, v69, 16, 1
	v_add_co_u32_e32 v72, vcc, s0, v128
	v_lshrrev_b32_e32 v1, 16, v1
	v_add3_u32 v67, v69, v67, s63
	v_addc_co_u32_e32 v73, vcc, 0, v129, vcc
	v_and_or_b32 v67, v67, s60, v1
	v_lshl_add_u64 v[148:149], v[148:149], 0, s[20:21]
	global_store_dwordx2 v[134:135], v[126:127], off sc0 sc1
	global_store_dwordx2 v[134:135], v[122:123], off offset:128 sc0 sc1
	global_store_dwordx2 v[120:121], v[118:119], off sc0 sc1
	global_store_dwordx2 v[120:121], v[114:115], off offset:128 sc0 sc1
	global_store_dwordx2 v[112:113], v[110:111], off sc0 sc1
	global_store_dwordx2 v[112:113], v[106:107], off offset:128 sc0 sc1
	global_store_dwordx2 v[104:105], v[102:103], off sc0 sc1
	global_store_dwordx2 v[104:105], v[98:99], off offset:128 sc0 sc1
	global_store_dwordx2 v[96:97], v[94:95], off sc0 sc1
	global_store_dwordx2 v[96:97], v[90:91], off offset:128 sc0 sc1
	global_store_dwordx2 v[88:89], v[86:87], off sc0 sc1
	global_store_dwordx2 v[88:89], v[82:83], off offset:128 sc0 sc1
	global_store_dwordx2 v[80:81], v[78:79], off sc0 sc1
	global_store_dwordx2 v[80:81], v[74:75], off offset:128 sc0 sc1
	global_store_dwordx2 v[72:73], v[70:71], off sc0 sc1
	global_store_dwordx2 v[72:73], v[66:67], off offset:128 sc0 sc1
	s_cbranch_scc0 .LBB0_225
